# baseline with only the final y stores changed from nt to plain
# speedup vs baseline: 1.0153x; 1.0153x over previous
.LBB0_530:
	v_lshl_add_u64 v[130:131], v[130:131], 2, s[10:11]
	global_load_dword v170, v[130:131], off sc1
	v_mov_b32_e32 v178, 0x3727c5ac
	v_lshl_add_u64 v[132:133], s[66:67], 0, v[132:133]
	v_lshlrev_b64 v[128:129], 2, v[128:129]
	v_lshl_add_u64 v[132:133], v[132:133], 0, v[128:129]
	v_lshl_add_u64 v[136:137], v[136:137], 2, s[10:11]
	s_waitcnt vmcnt(0)
	v_fmamk_f32 v170, v170, 0x3a800000, v178
	v_rsq_f32_e32 v170, v170
	s_nop 0
	v_pk_mul_f32 v[124:125], v[124:125], v[170:171] op_sel_hi:[1,0]
	v_pk_mul_f32 v[126:127], v[126:127], v[170:171] op_sel_hi:[1,0]
	v_pk_mul_f32 v[120:121], v[120:121], v[170:171] op_sel_hi:[1,0]
	v_pk_mul_f32 v[122:123], v[122:123], v[170:171] op_sel_hi:[1,0]
	v_pk_mul_f32 v[172:173], v[116:117], v[170:171] op_sel_hi:[1,0]
	v_pk_mul_f32 v[174:175], v[118:119], v[170:171] op_sel_hi:[1,0]
	v_pk_mul_f32 v[176:177], v[112:113], v[170:171] op_sel_hi:[1,0]
	v_pk_mul_f32 v[170:171], v[114:115], v[170:171] op_sel_hi:[1,0]
	v_pk_mul_f32 v[114:115], v[14:15], v[126:127]
	v_pk_mul_f32 v[112:113], v[12:13], v[124:125]
	v_pk_mul_f32 v[118:119], v[10:11], v[122:123]
	v_pk_mul_f32 v[116:117], v[8:9], v[120:121]
	v_pk_mul_f32 v[122:123], v[6:7], v[174:175]
	v_pk_mul_f32 v[120:121], v[4:5], v[172:173]
	v_pk_mul_f32 v[126:127], v[2:3], v[170:171]
	v_pk_mul_f32 v[124:125], v[0:1], v[176:177]
	global_store_dwordx4 v[132:133], v[112:115], off
	global_store_dwordx4 v[132:133], v[116:119], off offset:64
	global_store_dwordx4 v[132:133], v[120:123], off offset:512
	global_store_dwordx4 v[132:133], v[124:127], off offset:576
	global_load_dword v112, v[136:137], off sc1
	v_lshl_add_u64 v[114:115], s[66:67], 0, v[134:135]
	v_lshl_add_u64 v[114:115], v[114:115], 0, v[128:129]
	v_lshl_add_u64 v[116:117], v[140:141], 2, s[10:11]
	s_waitcnt vmcnt(0)
	v_fmamk_f32 v112, v112, 0x3a800000, v178
	v_rsq_f32_e32 v112, v112
	s_nop 0
	v_pk_mul_f32 v[108:109], v[108:109], v[112:113] op_sel_hi:[1,0]
	v_pk_mul_f32 v[110:111], v[110:111], v[112:113] op_sel_hi:[1,0]
	v_pk_mul_f32 v[104:105], v[104:105], v[112:113] op_sel_hi:[1,0]
	v_pk_mul_f32 v[106:107], v[106:107], v[112:113] op_sel_hi:[1,0]
	v_pk_mul_f32 v[118:119], v[100:101], v[112:113] op_sel_hi:[1,0]
	v_pk_mul_f32 v[120:121], v[102:103], v[112:113] op_sel_hi:[1,0]
	v_pk_mul_f32 v[122:123], v[96:97], v[112:113] op_sel_hi:[1,0]
	v_pk_mul_f32 v[112:113], v[98:99], v[112:113] op_sel_hi:[1,0]
	v_pk_mul_f32 v[98:99], v[14:15], v[110:111]
	v_pk_mul_f32 v[96:97], v[12:13], v[108:109]
	v_pk_mul_f32 v[102:103], v[10:11], v[106:107]
	v_pk_mul_f32 v[100:101], v[8:9], v[104:105]
	v_pk_mul_f32 v[106:107], v[6:7], v[120:121]
	v_pk_mul_f32 v[104:105], v[4:5], v[118:119]
	v_pk_mul_f32 v[110:111], v[2:3], v[112:113]
	v_pk_mul_f32 v[108:109], v[0:1], v[122:123]
	global_store_dwordx4 v[114:115], v[96:99], off
	global_store_dwordx4 v[114:115], v[100:103], off offset:64
	global_store_dwordx4 v[114:115], v[104:107], off offset:512
	global_store_dwordx4 v[114:115], v[108:111], off offset:576
	global_load_dword v96, v[116:117], off sc1
	v_lshl_add_u64 v[98:99], s[66:67], 0, v[138:139]
	v_lshl_add_u64 v[98:99], v[98:99], 0, v[128:129]
	v_lshl_add_u64 v[100:101], v[144:145], 2, s[10:11]
	s_waitcnt vmcnt(0)
	v_fmamk_f32 v96, v96, 0x3a800000, v178
	v_rsq_f32_e32 v96, v96
	s_nop 0
	v_pk_mul_f32 v[92:93], v[92:93], v[96:97] op_sel_hi:[1,0]
	v_pk_mul_f32 v[94:95], v[94:95], v[96:97] op_sel_hi:[1,0]
	v_pk_mul_f32 v[88:89], v[88:89], v[96:97] op_sel_hi:[1,0]
	v_pk_mul_f32 v[90:91], v[90:91], v[96:97] op_sel_hi:[1,0]
	v_pk_mul_f32 v[102:103], v[84:85], v[96:97] op_sel_hi:[1,0]
	v_pk_mul_f32 v[104:105], v[86:87], v[96:97] op_sel_hi:[1,0]
	v_pk_mul_f32 v[106:107], v[80:81], v[96:97] op_sel_hi:[1,0]
	v_pk_mul_f32 v[96:97], v[82:83], v[96:97] op_sel_hi:[1,0]
	v_pk_mul_f32 v[82:83], v[14:15], v[94:95]
	v_pk_mul_f32 v[80:81], v[12:13], v[92:93]
	v_pk_mul_f32 v[86:87], v[10:11], v[90:91]
	v_pk_mul_f32 v[84:85], v[8:9], v[88:89]
	v_pk_mul_f32 v[90:91], v[6:7], v[104:105]
	v_pk_mul_f32 v[88:89], v[4:5], v[102:103]
	v_pk_mul_f32 v[94:95], v[2:3], v[96:97]
	v_pk_mul_f32 v[92:93], v[0:1], v[106:107]
	global_store_dwordx4 v[98:99], v[80:83], off
	global_store_dwordx4 v[98:99], v[84:87], off offset:64
	global_store_dwordx4 v[98:99], v[88:91], off offset:512
	global_store_dwordx4 v[98:99], v[92:95], off offset:576
	global_load_dword v80, v[100:101], off sc1
	v_lshl_add_u64 v[82:83], s[66:67], 0, v[142:143]
	v_lshl_add_u64 v[82:83], v[82:83], 0, v[128:129]
	s_waitcnt vmcnt(0)
	v_fmamk_f32 v80, v80, 0x3a800000, v178
	v_rsq_f32_e32 v80, v80
	s_nop 0
	v_pk_mul_f32 v[84:85], v[146:147], v[80:81] op_sel_hi:[1,0]
	v_pk_mul_f32 v[78:79], v[78:79], v[80:81] op_sel_hi:[1,0]
	v_pk_mul_f32 v[76:77], v[76:77], v[80:81] op_sel_hi:[1,0]
	v_pk_mul_f32 v[74:75], v[74:75], v[80:81] op_sel_hi:[1,0]
	v_pk_mul_f32 v[86:87], v[68:69], v[80:81] op_sel_hi:[1,0]
	v_pk_mul_f32 v[88:89], v[70:71], v[80:81] op_sel_hi:[1,0]
	v_pk_mul_f32 v[90:91], v[64:65], v[80:81] op_sel_hi:[1,0]
	v_pk_mul_f32 v[80:81], v[66:67], v[80:81] op_sel_hi:[1,0]
	v_pk_mul_f32 v[66:67], v[14:15], v[78:79]
	v_pk_mul_f32 v[64:65], v[12:13], v[84:85]
	v_pk_mul_f32 v[70:71], v[10:11], v[74:75]
	v_pk_mul_f32 v[68:69], v[8:9], v[76:77]
	v_pk_mul_f32 v[76:77], v[6:7], v[88:89]
	v_pk_mul_f32 v[74:75], v[4:5], v[86:87]
	v_pk_mul_f32 v[80:81], v[2:3], v[80:81]
	v_pk_mul_f32 v[78:79], v[0:1], v[90:91]
	global_store_dwordx4 v[82:83], v[64:67], off
	global_store_dwordx4 v[82:83], v[68:71], off offset:64
	global_store_dwordx4 v[82:83], v[74:77], off offset:512
	global_store_dwordx4 v[82:83], v[78:81], off offset:576
	global_load_dword v64, v[130:131], off offset:512 sc1
	v_lshl_add_u64 v[66:67], s[66:67], 0, v[72:73]
	v_lshl_add_u64 v[66:67], v[66:67], 0, v[128:129]
	s_waitcnt vmcnt(0)
	v_fmamk_f32 v64, v64, 0x3a800000, v178
	v_rsq_f32_e32 v64, v64
	s_nop 0
	v_pk_mul_f32 v[68:69], v[148:149], v[64:65] op_sel_hi:[1,0]
	v_pk_mul_f32 v[62:63], v[62:63], v[64:65] op_sel_hi:[1,0]
	v_pk_mul_f32 v[60:61], v[60:61], v[64:65] op_sel_hi:[1,0]
	v_pk_mul_f32 v[58:59], v[58:59], v[64:65] op_sel_hi:[1,0]
	v_pk_mul_f32 v[70:71], v[52:53], v[64:65] op_sel_hi:[1,0]
	v_pk_mul_f32 v[72:73], v[54:55], v[64:65] op_sel_hi:[1,0]
	v_pk_mul_f32 v[74:75], v[48:49], v[64:65] op_sel_hi:[1,0]
	v_pk_mul_f32 v[64:65], v[50:51], v[64:65] op_sel_hi:[1,0]
	v_pk_mul_f32 v[50:51], v[14:15], v[62:63]
	v_pk_mul_f32 v[48:49], v[12:13], v[68:69]
	v_pk_mul_f32 v[54:55], v[10:11], v[58:59]
	v_pk_mul_f32 v[52:53], v[8:9], v[60:61]
	v_pk_mul_f32 v[60:61], v[6:7], v[72:73]
	v_pk_mul_f32 v[58:59], v[4:5], v[70:71]
	v_pk_mul_f32 v[64:65], v[2:3], v[64:65]
	v_pk_mul_f32 v[62:63], v[0:1], v[74:75]
	global_store_dwordx4 v[66:67], v[48:51], off
	global_store_dwordx4 v[66:67], v[52:55], off offset:64
	global_store_dwordx4 v[66:67], v[58:61], off offset:512
	global_store_dwordx4 v[66:67], v[62:65], off offset:576
	global_load_dword v48, v[130:131], off offset:576 sc1
	v_lshl_add_u64 v[50:51], s[66:67], 0, v[56:57]
	v_lshl_add_u64 v[50:51], v[50:51], 0, v[128:129]
	s_waitcnt vmcnt(0)
	v_fmamk_f32 v48, v48, 0x3a800000, v178
	v_rsq_f32_e32 v48, v48
	s_nop 0
	v_pk_mul_f32 v[52:53], v[150:151], v[48:49] op_sel_hi:[1,0]
	v_pk_mul_f32 v[46:47], v[46:47], v[48:49] op_sel_hi:[1,0]
	v_pk_mul_f32 v[44:45], v[44:45], v[48:49] op_sel_hi:[1,0]
	v_pk_mul_f32 v[42:43], v[42:43], v[48:49] op_sel_hi:[1,0]
	v_pk_mul_f32 v[54:55], v[36:37], v[48:49] op_sel_hi:[1,0]
	v_pk_mul_f32 v[56:57], v[38:39], v[48:49] op_sel_hi:[1,0]
	v_pk_mul_f32 v[58:59], v[32:33], v[48:49] op_sel_hi:[1,0]
	v_pk_mul_f32 v[48:49], v[34:35], v[48:49] op_sel_hi:[1,0]
	v_pk_mul_f32 v[34:35], v[14:15], v[46:47]
	v_pk_mul_f32 v[32:33], v[12:13], v[52:53]
	v_pk_mul_f32 v[38:39], v[10:11], v[42:43]
	v_pk_mul_f32 v[36:37], v[8:9], v[44:45]
	v_pk_mul_f32 v[44:45], v[6:7], v[56:57]
	v_pk_mul_f32 v[42:43], v[4:5], v[54:55]
	v_pk_mul_f32 v[48:49], v[2:3], v[48:49]
	v_pk_mul_f32 v[46:47], v[0:1], v[58:59]
	global_store_dwordx4 v[50:51], v[32:35], off
	global_store_dwordx4 v[50:51], v[36:39], off offset:64
	global_store_dwordx4 v[50:51], v[42:45], off offset:512
	global_store_dwordx4 v[50:51], v[46:49], off offset:576
	global_load_dword v32, v[130:131], off offset:640 sc1
	v_lshl_add_u64 v[34:35], s[66:67], 0, v[40:41]
	v_lshl_add_u64 v[34:35], v[34:35], 0, v[128:129]
	s_waitcnt vmcnt(0)
	v_fmamk_f32 v32, v32, 0x3a800000, v178
	v_rsq_f32_e32 v32, v32
	s_nop 0
	v_pk_mul_f32 v[36:37], v[152:153], v[32:33] op_sel_hi:[1,0]
	v_pk_mul_f32 v[30:31], v[30:31], v[32:33] op_sel_hi:[1,0]
	v_pk_mul_f32 v[28:29], v[28:29], v[32:33] op_sel_hi:[1,0]
	v_pk_mul_f32 v[26:27], v[26:27], v[32:33] op_sel_hi:[1,0]
	v_pk_mul_f32 v[38:39], v[20:21], v[32:33] op_sel_hi:[1,0]
	v_pk_mul_f32 v[40:41], v[22:23], v[32:33] op_sel_hi:[1,0]
	v_pk_mul_f32 v[42:43], v[16:17], v[32:33] op_sel_hi:[1,0]
	v_pk_mul_f32 v[32:33], v[18:19], v[32:33] op_sel_hi:[1,0]
	v_pk_mul_f32 v[18:19], v[14:15], v[30:31]
	v_pk_mul_f32 v[16:17], v[12:13], v[36:37]
	v_pk_mul_f32 v[22:23], v[10:11], v[26:27]
	v_pk_mul_f32 v[20:21], v[8:9], v[28:29]
	v_pk_mul_f32 v[28:29], v[6:7], v[40:41]
	v_pk_mul_f32 v[26:27], v[4:5], v[38:39]
	v_pk_mul_f32 v[32:33], v[2:3], v[32:33]
	v_pk_mul_f32 v[30:31], v[0:1], v[42:43]
	global_store_dwordx4 v[34:35], v[16:19], off
	global_store_dwordx4 v[34:35], v[20:23], off offset:64
	global_store_dwordx4 v[34:35], v[26:29], off offset:512
	global_store_dwordx4 v[34:35], v[30:33], off offset:576
	global_load_dword v16, v[130:131], off offset:704 sc1
	v_lshl_add_u64 v[18:19], s[66:67], 0, v[24:25]
	v_lshl_add_u64 v[18:19], v[18:19], 0, v[128:129]
	s_waitcnt vmcnt(0)
	v_fmac_f32_e32 v178, 0x3a800000, v16
	v_rsq_f32_e32 v16, v178
	s_nop 0
	v_pk_mul_f32 v[20:21], v[168:169], v[16:17] op_sel_hi:[1,0]
	v_pk_mul_f32 v[22:23], v[166:167], v[16:17] op_sel_hi:[1,0]
	v_pk_mul_f32 v[24:25], v[164:165], v[16:17] op_sel_hi:[1,0]
	v_pk_mul_f32 v[26:27], v[162:163], v[16:17] op_sel_hi:[1,0]
	v_pk_mul_f32 v[28:29], v[160:161], v[16:17] op_sel_hi:[1,0]
	v_pk_mul_f32 v[30:31], v[158:159], v[16:17] op_sel_hi:[1,0]
	v_pk_mul_f32 v[32:33], v[156:157], v[16:17] op_sel_hi:[1,0]
	v_pk_mul_f32 v[16:17], v[154:155], v[16:17] op_sel_hi:[1,0]
	v_pk_mul_f32 v[14:15], v[14:15], v[22:23]
	v_pk_mul_f32 v[12:13], v[12:13], v[20:21]
	v_pk_mul_f32 v[10:11], v[10:11], v[26:27]
	v_pk_mul_f32 v[8:9], v[8:9], v[24:25]
	v_pk_mul_f32 v[6:7], v[6:7], v[30:31]
	v_pk_mul_f32 v[4:5], v[4:5], v[28:29]
	v_pk_mul_f32 v[2:3], v[2:3], v[16:17]
	v_pk_mul_f32 v[0:1], v[0:1], v[32:33]
	global_store_dwordx4 v[18:19], v[12:15], off
	global_store_dwordx4 v[18:19], v[8:11], off offset:64
	global_store_dwordx4 v[18:19], v[4:7], off offset:512
	global_store_dwordx4 v[18:19], v[0:3], off offset:576
